# P8: workgroups that own a sixth-round unit skip the DN-conversion work queue (no contended dequeue at the end of the phase)
# baseline (speedup 1.0000x reference)
.LBB0_239:
	v_readlane_b32 s0, v255, 13
	s_nop 3
	s_cmpk_lt_u32 s0, 0xac
	s_cbranch_scc1 .Ldc8_back
	s_branch .Ldc8_entry
